# mla_finalize token loop: the seven row loads of a token are issued together at the top of the iteration instead of one per memory round trip
# speedup vs baseline: 1.0916x; 1.0023x over previous
; DI float bf2f(u16 v) { return __uint_as_float(((unsigned)v) << 16); }
; DI void mla_finalize(const P& p, char* smem, int vb, int nvb) {
;     ...
;   for (int t = vb * 4 + wave; t < T; t += nvb * 4) {
;     float f[8];
;     {
;       uint4 v = *(const uint4*)(Q + (size_t)t * 768 + lane * 8);
;       unpack8(v, f);
; #pragma unroll
;       for (int j = 0; j < 8; ++j) sq[lane * 8 + j] = f[j];
;       if (lane < 32) {
;         v = *(const uint4*)(Q + (size_t)t * 768 + (lane + 64) * 8);
;         unpack8(v, f);
; #pragma unroll
;         for (int j = 0; j < 8; ++j) sq[(lane + 64) * 8 + j] = f[j];
;       }
;     }
;     uint4 kv0 = *(const uint4*)(KV + (size_t)t * 1024 + lane * 8);
;     uint4 kv1 = *(const uint4*)(KV + (size_t)t * 1024 + (lane + 64) * 8);
;     unpack8(kv0, f);
; #pragma unroll
;     for (int j = 0; j < 8; ++j) skv[lane * 8 + j] = f[j];
;     unpack8(kv1, f);
; #pragma unroll
;     for (int j = 0; j < 8; ++j) skv[(lane + 64) * 8 + j] = f[j];
;     if (lane < 32) skr[lane] = bf2f(z[(size_t)t * EVEN_IN + 640 + lane]);
;     float ssq = 0.f, sskv = 0.f;
;     if (lane < 48) {
;       uint4 v = *(const uint4*)(z + (size_t)t * EVEN_IN + lane * 8);
;       unpack8(v, f);
; #pragma unroll
;       for (int j = 0; j < 8; ++j) ssq += f[j] * f[j];
;     }
;     if (lane < 32) {
;       uint4 v = *(const uint4*)(z + (size_t)t * EVEN_IN + 384 + lane * 8);
;       unpack8(v, f);
; #pragma unroll
;       for (int j = 0; j < 8; ++j) sskv += f[j] * f[j];
;     }
.LBB0_1036:
	s_waitcnt vmcnt(25)
	v_lshl_add_u64 v[48:49], s[70:71], 0, v[42:43]
	v_add_co_u32_e32 v0, vcc, 0xbb72000, v48
	s_nop 1
	v_addc_co_u32_e32 v1, vcc, 0, v49, vcc
	global_load_dwordx4 v[224:227], v[0:1], off
	v_lshl_add_u64 v[250:251], s[70:71], 0, v[46:47]
	global_load_dwordx4 v[232:235], v[250:251], off offset:-1024
	global_load_dwordx4 v[236:239], v[250:251], off
	v_lshl_add_u64 v[250:251], s[70:71], 0, v[40:41]
	v_lshl_add_u64 v[252:253], s[70:71], 0, v[44:45]
	s_and_saveexec_b64 s[44:45], s[0:1]
	global_load_dwordx4 v[228:231], v[0:1], off offset:1024
	global_load_ushort v240, v[250:251], off
	global_load_dwordx4 v[246:249], v[252:253], off
	s_or_b64 exec, exec, s[44:45]
	s_and_saveexec_b64 s[44:45], s[38:39]
	global_load_dwordx4 v[242:245], v[252:253], off offset:-768
	s_or_b64 exec, exec, s[44:45]
	s_waitcnt vmcnt(6)
	v_lshlrev_b32_e32 v10, 16, v227
	v_lshlrev_b32_e32 v8, 16, v226
	v_and_b32_e32 v11, 0xffff0000, v227
	v_and_b32_e32 v9, 0xffff0000, v226
	v_lshlrev_b32_e32 v6, 16, v225
	v_lshlrev_b32_e32 v4, 16, v224
	v_and_b32_e32 v7, 0xffff0000, v225
	v_and_b32_e32 v5, 0xffff0000, v224
	ds_write_b128 v74, v[8:11] offset:16
	ds_write_b128 v74, v[4:7]
	s_and_saveexec_b64 s[44:45], s[0:1]
	s_cbranch_execz .LBB0_1038
	v_add_co_u32_e32 v0, vcc, 0xbb72000, v48
	s_nop 1
	v_addc_co_u32_e32 v1, vcc, 0, v49, vcc
	s_waitcnt vmcnt(3)
	v_lshlrev_b32_e32 v10, 16, v231
	v_lshlrev_b32_e32 v8, 16, v230
	v_and_b32_e32 v11, 0xffff0000, v231
	v_and_b32_e32 v9, 0xffff0000, v230
	v_lshlrev_b32_e32 v6, 16, v229
	v_lshlrev_b32_e32 v4, 16, v228
	v_and_b32_e32 v7, 0xffff0000, v229
	v_and_b32_e32 v5, 0xffff0000, v228
	ds_write_b128 v74, v[8:11] offset:2064
	ds_write_b128 v74, v[4:7] offset:2048
.LBB0_1038:
	s_or_b64 exec, exec, s[44:45]
	v_lshl_add_u64 v[50:51], s[70:71], 0, v[46:47]
	s_waitcnt vmcnt(5)
	v_lshlrev_b32_e32 v0, 16, v232
	v_and_b32_e32 v1, 0xffff0000, v232
	v_lshlrev_b32_e32 v2, 16, v233
	v_and_b32_e32 v3, 0xffff0000, v233
	v_lshlrev_b32_e32 v4, 16, v234
	v_and_b32_e32 v5, 0xffff0000, v234
	v_lshlrev_b32_e32 v6, 16, v235
	v_and_b32_e32 v7, 0xffff0000, v235
	s_waitcnt vmcnt(4)
	v_lshlrev_b32_e32 v8, 16, v236
	v_and_b32_e32 v9, 0xffff0000, v236
	v_lshlrev_b32_e32 v10, 16, v237
	v_and_b32_e32 v11, 0xffff0000, v237
	v_lshlrev_b32_e32 v12, 16, v238
	v_and_b32_e32 v13, 0xffff0000, v238
	v_lshlrev_b32_e32 v14, 16, v239
	v_and_b32_e32 v15, 0xffff0000, v239
	ds_write_b128 v74, v[0:3] offset:3072
	ds_write_b128 v74, v[4:7] offset:3088
	ds_write_b128 v74, v[8:11] offset:5120
	ds_write_b128 v74, v[12:15] offset:5136
	s_and_saveexec_b64 s[44:45], s[0:1]
	s_cbranch_execz .LBB0_1040
	v_lshl_add_u64 v[52:53], s[70:71], 0, v[40:41]
	s_waitcnt vmcnt(2)
	v_lshlrev_b32_e32 v52, 16, v240
	ds_write_b32 v84, v52 offset:7168
.LBB0_1040:
	s_or_b64 exec, exec, s[44:45]
	v_mov_b32_e32 v52, 0
	v_lshl_add_u64 v[54:55], s[70:71], 0, v[44:45]
	v_mov_b32_e32 v53, 0
	s_and_saveexec_b64 s[44:45], s[38:39]
	s_cbranch_execz .LBB0_1042
	s_waitcnt vmcnt(0)
	v_lshlrev_b32_e32 v60, 16, v242
	v_and_b32_e32 v61, 0xffff0000, v242
	v_lshlrev_b32_e32 v63, 16, v243
	v_and_b32_e32 v62, 0xffff0000, v243
	v_lshlrev_b32_e32 v57, 16, v244
	v_and_b32_e32 v56, 0xffff0000, v244
	v_lshlrev_b32_e32 v65, 16, v245
	v_and_b32_e32 v64, 0xffff0000, v245
	v_pk_mul_f32 v[58:59], v[60:61], v[60:61]
	v_pk_mul_f32 v[60:61], v[62:63], v[62:63]
	v_add_f32_e32 v53, v58, v59
	v_add_f32_e32 v53, v53, v61
	v_pk_mul_f32 v[56:57], v[56:57], v[56:57]
	v_add_f32_e32 v53, v60, v53
	v_add_f32_e32 v53, v57, v53
	v_pk_mul_f32 v[62:63], v[64:65], v[64:65]
	v_add_f32_e32 v53, v56, v53
	v_add_f32_e32 v53, v63, v53
	v_add_f32_e32 v53, v62, v53
.LBB0_1042:
	s_or_b64 exec, exec, s[44:45]
	s_and_saveexec_b64 s[44:45], s[0:1]
	s_cbranch_execz .LBB0_1044
	s_waitcnt vmcnt(0)
	v_lshlrev_b32_e32 v58, 16, v246
	v_and_b32_e32 v59, 0xffff0000, v246
	v_lshlrev_b32_e32 v61, 16, v247
	v_and_b32_e32 v60, 0xffff0000, v247
	v_lshlrev_b32_e32 v55, 16, v248
	v_and_b32_e32 v54, 0xffff0000, v248
	v_lshlrev_b32_e32 v63, 16, v249
	v_and_b32_e32 v62, 0xffff0000, v249
	v_pk_mul_f32 v[56:57], v[58:59], v[58:59]
	v_pk_mul_f32 v[58:59], v[60:61], v[60:61]
	v_add_f32_e32 v52, v56, v57
	v_add_f32_e32 v52, v52, v59
	v_pk_mul_f32 v[54:55], v[54:55], v[54:55]
	v_add_f32_e32 v52, v58, v52
	v_add_f32_e32 v52, v55, v52
	v_pk_mul_f32 v[60:61], v[62:63], v[62:63]
	v_add_f32_e32 v52, v54, v52
	v_add_f32_e32 v52, v61, v52
	v_add_f32_e32 v52, v60, v52
